# fast loop: loop-edge rotation (scalar bookkeeping and loop-carried moves in front of the barriers, one-branch back edge + exit stub), MFMA-first step heads
# speedup vs baseline: 1.0025x; 1.0025x over previous
; #define WAIT_BAR(N) asm volatile("s_waitcnt vmcnt(" #N ") lgkmcnt(0)\n\ts_barrier":::"memory")
;   #define RESC() do{ if(resc){ asm volatile("s_waitcnt lgkmcnt(0)":::"memory"); \
;       _Pragma("unroll") for(int d_=0;d_<2;++d_) _Pragma("unroll") for(int r=0;r<16;++r)o[d_][r]*=wsf[crow(r,hi)]; } }while(0)
;   #define ROT() do{sl_prev=sl_cur;sl_cur=sl_next;sl_next=(sl_next==(NSLOT-1)*SLOTB)?0:sl_next+SLOTB;}while(0)
;     ...
;   int t=1;
;     ...
;   for(;t+5<NT;t+=2){
;     STEP(pB0,pB1,pA0,pA1,t,true,true,true);     WAIT_BAR(2); RESC(); ROT();
;     STEP(pA0,pA1,pB0,pB1,t+1,true,true,true);   WAIT_BAR(2); RESC(); ROT();
.Lfb_loop:
	v_mfma_f32_32x32x16_bf16 v[96:111], v[174:177], v[134:137], v[32:47]
	v_add_u32_e32 v183, s0, v211
	ds_read_b64_tr_b16 v[178:179], v183 offset:24576
	ds_read_b64_tr_b16 v[180:181], v183 offset:25088
	v_add_f32_e32 v80, v64, v65
	v_add_f32_e32 v80, v66, v80
	v_add_f32_e32 v80, v67, v80
	v_add_f32_e32 v80, v68, v80
	v_add_f32_e32 v80, v69, v80
	v_cvt_pk_bf16_f32 v142, v64, v65
	v_cvt_pk_bf16_f32 v143, v66, v67
	ds_read_b64_tr_b16 v[174:175], v183 offset:28672
	ds_read_b64_tr_b16 v[176:177], v183 offset:29184
	v_add_f32_e32 v64, v70, v80
	v_mfma_f32_32x32x16_bf16 v[80:95], v[170:173], v[134:137], v[32:47]
	v_add_f32_e32 v64, v71, v64
	v_add_f32_e32 v64, v72, v64
	v_add_f32_e32 v126, v73, v64
	v_cvt_pk_bf16_f32 v144, v68, v69
	v_cvt_pk_bf16_f32 v145, v70, v71
	ds_read_b64_tr_b16 v[64:65], v183 offset:25600
	ds_read_b64_tr_b16 v[66:67], v183 offset:26112
	v_mfma_f32_32x32x16_bf16 v[96:111], v[166:169], v[122:125], v[96:111]
	v_add_f32_e32 v68, v74, v126
	v_add_f32_e32 v68, v75, v68
	v_add_f32_e32 v68, v76, v68
	v_add_f32_e32 v126, v77, v68
	v_cvt_pk_bf16_f32 v138, v72, v73
	v_cvt_pk_bf16_f32 v139, v74, v75
	ds_read_b64_tr_b16 v[68:69], v183 offset:29696
	ds_read_b64_tr_b16 v[70:71], v183 offset:30208
	v_mfma_f32_32x32x16_bf16 v[80:95], v[162:165], v[122:125], v[80:95]
	v_add_f32_e32 v72, v78, v126
	v_add_f32_e32 v72, v79, v72
	v_add_f32_e32 v72, v48, v72
	v_add_f32_e32 v126, v49, v72
	v_cvt_pk_bf16_f32 v140, v76, v77
	v_cvt_pk_bf16_f32 v141, v78, v79
	ds_read_b64_tr_b16 v[72:73], v183 offset:26624
	ds_read_b64_tr_b16 v[74:75], v183 offset:27136
	v_mfma_f32_32x32x16_bf16 v[96:111], v[158:161], v[118:121], v[96:111]
	v_add_f32_e32 v76, v50, v126
	v_add_f32_e32 v76, v51, v76
	v_add_f32_e32 v76, v52, v76
	v_add_f32_e32 v76, v53, v76
	v_cvt_pk_bf16_f32 v130, v48, v49
	v_cvt_pk_bf16_f32 v131, v50, v51
	ds_read_b64_tr_b16 v[48:49], v183 offset:30720
	ds_read_b64_tr_b16 v[50:51], v183 offset:31232
	v_mfma_f32_32x32x16_bf16 v[80:95], v[154:157], v[118:121], v[80:95]
	v_add_f32_e32 v76, v54, v76
	v_add_f32_e32 v76, v55, v76
	v_add_f32_e32 v76, v56, v76
	v_add_f32_e32 v76, v57, v76
	v_cvt_pk_bf16_f32 v132, v52, v53
	v_cvt_pk_bf16_f32 v133, v54, v55
	ds_read_b64_tr_b16 v[52:53], v183 offset:27648
	ds_read_b64_tr_b16 v[54:55], v183 offset:28160
	v_mfma_f32_32x32x16_bf16 v[96:111], v[150:153], v[114:117], v[96:111]
	v_add_f32_e32 v76, v58, v76
	v_add_f32_e32 v76, v59, v76
	v_add_f32_e32 v76, v60, v76
	v_add_f32_e32 v76, v61, v76
	v_cvt_pk_bf16_f32 v126, v56, v57
	v_cvt_pk_bf16_f32 v127, v58, v59
	ds_read_b64_tr_b16 v[56:57], v183 offset:31744
	ds_read_b64_tr_b16 v[58:59], v183 offset:32256
	v_mfma_f32_32x32x16_bf16 v[80:95], v[146:149], v[114:117], v[80:95]
	v_add_f32_e32 v76, v62, v76
	v_add_f32_e32 v76, v63, v76
	v_cvt_pk_bf16_f32 v128, v60, v61
	v_cvt_pk_bf16_f32 v129, v62, v63
	s_add_i32 m0, s24, s69
	v_add_f32_e32 v185, v222, v76
	global_load_lds_dwordx4 v188, s[2:3]
	s_add_i32 m0, s13, s70
	s_add_u32 s2, s2, 0x58000
	global_load_lds_dwordx4 v186, s[26:27]
	s_addc_u32 s3, s3, 0
	s_add_u32 s26, s26, 0x58000
	s_addc_u32 s27, s27, 0
	s_waitcnt lgkmcnt(8)
	v_mfma_f32_32x32x16_bf16 v[16:31], v[142:145], v[178:181], v[16:31]
	v_exp_f32_e32 v96, v96
	v_exp_f32_e32 v97, v97
	v_exp_f32_e32 v98, v98
	v_exp_f32_e32 v99, v99
	v_mfma_f32_32x32x16_bf16 v[0:15], v[142:145], v[174:177], v[0:15]
	v_exp_f32_e32 v100, v100
	v_exp_f32_e32 v101, v101
	v_exp_f32_e32 v102, v102
	v_exp_f32_e32 v103, v103
	v_add_u32_e32 v76, s13, v210
	ds_read_b128 v[60:63], v76
	ds_read_b128 v[174:177], v76 offset:512
	v_mfma_f32_32x32x16_bf16 v[16:31], v[138:141], v[64:67], v[16:31]
	v_exp_f32_e32 v104, v104
	v_exp_f32_e32 v105, v105
	v_exp_f32_e32 v106, v106
	v_exp_f32_e32 v107, v107
	ds_read_b128 v[178:181], v76 offset:2048
	ds_read_b128 v[170:173], v76 offset:2560
	v_mfma_f32_32x32x16_bf16 v[0:15], v[138:141], v[68:71], v[0:15]
	v_exp_f32_e32 v108, v108
	v_exp_f32_e32 v109, v109
	v_exp_f32_e32 v110, v110
	v_exp_f32_e32 v111, v111
	ds_read_b128 v[166:169], v76 offset:4096
	ds_read_b128 v[162:165], v76 offset:4608
	s_waitcnt lgkmcnt(6)
	v_mfma_f32_32x32x16_bf16 v[16:31], v[130:133], v[72:75], v[16:31]
	v_exp_f32_e32 v80, v80
	v_exp_f32_e32 v81, v81
	v_exp_f32_e32 v82, v82
	v_exp_f32_e32 v83, v83
	ds_read_b128 v[158:161], v76 offset:6144
	ds_read_b128 v[154:157], v76 offset:6656
	v_mfma_f32_32x32x16_bf16 v[0:15], v[130:133], v[48:51], v[0:15]
	v_exp_f32_e32 v84, v84
	v_exp_f32_e32 v85, v85
	v_exp_f32_e32 v86, v86
	v_exp_f32_e32 v87, v87
	v_mfma_f32_32x32x16_bf16 v[16:31], v[126:129], v[52:55], v[16:31]
	v_exp_f32_e32 v88, v88
	v_exp_f32_e32 v89, v89
	v_exp_f32_e32 v90, v90
	v_exp_f32_e32 v91, v91
	v_mfma_f32_32x32x16_bf16 v[0:15], v[126:129], v[56:59], v[0:15]
	v_exp_f32_e32 v92, v92
	v_exp_f32_e32 v93, v93
	v_exp_f32_e32 v94, v94
	v_exp_f32_e32 v95, v95
	s_add_i32 s0, s13, 0x2000
	s_cmpk_lg_i32 s13, 0x4000
	s_cselect_b32 s72, s0, 0
	s_waitcnt vmcnt(2) lgkmcnt(0)
	s_barrier
; #define WAIT_BAR(N) asm volatile("s_waitcnt vmcnt(" #N ") lgkmcnt(0)\n\ts_barrier":::"memory")
;   #define RESC() do{ if(resc){ asm volatile("s_waitcnt lgkmcnt(0)":::"memory"); \
;       _Pragma("unroll") for(int d_=0;d_<2;++d_) _Pragma("unroll") for(int r=0;r<16;++r)o[d_][r]*=wsf[crow(r,hi)]; } }while(0)
;   #define ROT() do{sl_prev=sl_cur;sl_cur=sl_next;sl_next=(sl_next==(NSLOT-1)*SLOTB)?0:sl_next+SLOTB;}while(0)
;     ...
;   int t=1;
;     ...
;   for(;t+5<NT;t+=2){
;     STEP(pB0,pB1,pA0,pA1,t,true,true,true);     WAIT_BAR(2); RESC(); ROT();
;     STEP(pA0,pA1,pB0,pB1,t+1,true,true,true);   WAIT_BAR(2); RESC(); ROT();
	v_mfma_f32_32x32x16_bf16 v[64:79], v[60:63], v[134:137], v[32:47]
	v_add_u32_e32 v196, s24, v211
	ds_read_b64_tr_b16 v[150:151], v196 offset:24576
	ds_read_b64_tr_b16 v[152:153], v196 offset:25088
	v_add_f32_e32 v48, v96, v97
	v_add_f32_e32 v48, v98, v48
	v_add_f32_e32 v48, v99, v48
	v_add_f32_e32 v48, v100, v48
	v_add_f32_e32 v48, v101, v48
	v_cvt_pk_bf16_f32 v142, v96, v97
	v_cvt_pk_bf16_f32 v143, v98, v99
	ds_read_b64_tr_b16 v[146:147], v196 offset:28672
	ds_read_b64_tr_b16 v[148:149], v196 offset:29184
	v_add_f32_e32 v48, v102, v48
	v_add_f32_e32 v48, v103, v48
	v_add_f32_e32 v48, v104, v48
	v_add_f32_e32 v126, v105, v48
	v_mfma_f32_32x32x16_bf16 v[48:63], v[174:177], v[134:137], v[32:47]
	v_cvt_pk_bf16_f32 v144, v100, v101
	v_cvt_pk_bf16_f32 v145, v102, v103
	ds_read_b64_tr_b16 v[96:97], v196 offset:25600
	ds_read_b64_tr_b16 v[98:99], v196 offset:26112
	v_mfma_f32_32x32x16_bf16 v[64:79], v[178:181], v[122:125], v[64:79]
	v_add_f32_e32 v100, v106, v126
	v_add_f32_e32 v100, v107, v100
	v_add_f32_e32 v100, v108, v100
	v_add_f32_e32 v126, v109, v100
	v_cvt_pk_bf16_f32 v138, v104, v105
	v_cvt_pk_bf16_f32 v139, v106, v107
	ds_read_b64_tr_b16 v[100:101], v196 offset:29696
	ds_read_b64_tr_b16 v[102:103], v196 offset:30208
	v_mfma_f32_32x32x16_bf16 v[48:63], v[170:173], v[122:125], v[48:63]
	v_add_f32_e32 v104, v110, v126
	v_add_f32_e32 v104, v111, v104
	v_add_f32_e32 v104, v80, v104
	v_add_f32_e32 v126, v81, v104
	v_cvt_pk_bf16_f32 v140, v108, v109
	v_cvt_pk_bf16_f32 v141, v110, v111
	ds_read_b64_tr_b16 v[104:105], v196 offset:26624
	ds_read_b64_tr_b16 v[106:107], v196 offset:27136
	v_mfma_f32_32x32x16_bf16 v[64:79], v[166:169], v[118:121], v[64:79]
	v_add_f32_e32 v108, v82, v126
	v_add_f32_e32 v108, v83, v108
	v_add_f32_e32 v108, v84, v108
	v_add_f32_e32 v108, v85, v108
	v_cvt_pk_bf16_f32 v130, v80, v81
	v_cvt_pk_bf16_f32 v131, v82, v83
	ds_read_b64_tr_b16 v[80:81], v196 offset:30720
	ds_read_b64_tr_b16 v[82:83], v196 offset:31232
	v_mfma_f32_32x32x16_bf16 v[48:63], v[162:165], v[118:121], v[48:63]
	v_add_f32_e32 v108, v86, v108
	v_add_f32_e32 v108, v87, v108
	v_add_f32_e32 v108, v88, v108
	v_add_f32_e32 v108, v89, v108
	v_cvt_pk_bf16_f32 v132, v84, v85
	v_cvt_pk_bf16_f32 v133, v86, v87
	ds_read_b64_tr_b16 v[84:85], v196 offset:27648
	ds_read_b64_tr_b16 v[86:87], v196 offset:28160
	v_mfma_f32_32x32x16_bf16 v[64:79], v[158:161], v[114:117], v[64:79]
	v_add_f32_e32 v108, v90, v108
	v_add_f32_e32 v108, v91, v108
	v_add_f32_e32 v108, v92, v108
	v_add_f32_e32 v108, v93, v108
	v_cvt_pk_bf16_f32 v126, v88, v89
	v_cvt_pk_bf16_f32 v127, v90, v91
	ds_read_b64_tr_b16 v[88:89], v196 offset:31744
	ds_read_b64_tr_b16 v[90:91], v196 offset:32256
	v_mfma_f32_32x32x16_bf16 v[48:63], v[154:157], v[114:117], v[48:63]
	v_add_f32_e32 v108, v94, v108
	v_add_f32_e32 v108, v95, v108
	v_cvt_pk_bf16_f32 v128, v92, v93
	v_cvt_pk_bf16_f32 v129, v94, v95
	s_add_i32 m0, s13, s69
	v_add_f32_e32 v222, v185, v108
	global_load_lds_dwordx4 v188, s[2:3]
	s_add_i32 m0, s72, s70
	s_add_u32 s2, s2, 0x58000
	global_load_lds_dwordx4 v186, s[26:27]
	s_addc_u32 s3, s3, 0
	s_add_u32 s26, s26, 0x58000
	s_addc_u32 s27, s27, 0
	s_waitcnt lgkmcnt(8)
	v_mfma_f32_32x32x16_bf16 v[16:31], v[142:145], v[150:153], v[16:31]
	v_exp_f32_e32 v64, v64
	v_exp_f32_e32 v65, v65
	v_exp_f32_e32 v66, v66
	v_exp_f32_e32 v67, v67
	v_mfma_f32_32x32x16_bf16 v[0:15], v[142:145], v[146:149], v[0:15]
	v_exp_f32_e32 v68, v68
	v_exp_f32_e32 v69, v69
	v_exp_f32_e32 v70, v70
	v_exp_f32_e32 v71, v71
	v_add_u32_e32 v92, s72, v210
	ds_read_b128 v[174:177], v92
	ds_read_b128 v[170:173], v92 offset:512
	v_mfma_f32_32x32x16_bf16 v[16:31], v[138:141], v[96:99], v[16:31]
	v_exp_f32_e32 v72, v72
	v_exp_f32_e32 v73, v73
	v_exp_f32_e32 v74, v74
	v_exp_f32_e32 v75, v75
	ds_read_b128 v[166:169], v92 offset:2048
	ds_read_b128 v[162:165], v92 offset:2560
	v_mfma_f32_32x32x16_bf16 v[0:15], v[138:141], v[100:103], v[0:15]
	v_exp_f32_e32 v76, v76
	v_exp_f32_e32 v77, v77
	v_exp_f32_e32 v78, v78
	v_exp_f32_e32 v79, v79
	ds_read_b128 v[158:161], v92 offset:4096
	ds_read_b128 v[154:157], v92 offset:4608
	s_waitcnt lgkmcnt(6)
	v_mfma_f32_32x32x16_bf16 v[16:31], v[130:133], v[104:107], v[16:31]
	v_exp_f32_e32 v48, v48
	v_exp_f32_e32 v49, v49
	v_exp_f32_e32 v50, v50
	v_exp_f32_e32 v51, v51
	ds_read_b128 v[150:153], v92 offset:6144
	ds_read_b128 v[146:149], v92 offset:6656
	v_mfma_f32_32x32x16_bf16 v[0:15], v[130:133], v[80:83], v[0:15]
	v_exp_f32_e32 v52, v52
	v_exp_f32_e32 v53, v53
	v_exp_f32_e32 v54, v54
	v_exp_f32_e32 v55, v55
	v_mfma_f32_32x32x16_bf16 v[16:31], v[126:129], v[84:87], v[16:31]
	v_exp_f32_e32 v56, v56
	v_exp_f32_e32 v57, v57
	v_exp_f32_e32 v58, v58
	v_exp_f32_e32 v59, v59
	v_mfma_f32_32x32x16_bf16 v[0:15], v[126:129], v[88:91], v[0:15]
	v_exp_f32_e32 v60, v60
	v_exp_f32_e32 v61, v61
	v_exp_f32_e32 v62, v62
	v_exp_f32_e32 v63, v63
	s_add_i32 s0, s72, 0x2000
	s_cmpk_lg_i32 s72, 0x4000
	s_cselect_b32 s74, s0, 0
	s_add_i32 s0, s75, 2
	s_cmp_ge_u32 s0, s71
	s_mov_b32 s75, s0
	s_mov_b32 s0, s13
	s_mov_b32 s24, s72
	s_mov_b32 s13, s74
	s_waitcnt vmcnt(2) lgkmcnt(0)
	s_barrier
	s_cbranch_scc0 .Lfb_loop
	s_mov_b32 s13, s0
	s_add_i32 s75, s75, -2
	s_branch .LBB0_1231
